# R2/R3 fast bodies: the bf16 projection row is unpacked once and kept in registers (the scale chunk is read from LDS after the update half)
# speedup vs baseline: 1.0154x; 1.0026x over previous
; __device__ __forceinline__ unsigned pk2(float lo, float hi) { return pg8::cvt_pk_bf16(lo, hi); }
; __device__ __forceinline__ float bflo(unsigned w) { return __uint_as_float(w << 16); }
; __device__ __forceinline__ float bfhi(unsigned w) { return __uint_as_float(w & 0xffff0000u); }
; __device__ __forceinline__ void row_pass(const RowPass& R, int gw, int ngw, int lane) {
;     ...
;             if (R.update) {
;                 f32x4 y[4]; float ss = 0.f;
; #pragma unroll
;                 for (int j = 0; j < 4; ++j) { const u32x2 w = yw[k][j]; y[j] = (f32x4){bflo(w.x), bfhi(w.x), bflo(w.y), bfhi(w.y)};
;                     ss += (y[j][0] * y[j][0] + y[j][1] * y[j][1]) + (y[j][2] * y[j][2] + y[j][3] * y[j][3]); }
;                 const float rstd = __builtin_amdgcn_rsqf(wave_sum(ss) * (1.0f / DM) + EPS);
;                 const float* gate = R.mod + ((size_t)(R.lg * 9 + bb) * NMOD + R.gi) * DM;
; #pragma unroll
;                 for (int j = 0; j < 4; ++j) { const f32x4 g = *(const f32x4*)(gate + lane * 4 + 256 * j), gp = *(const f32x4*)(R.gpost + lane * 4 + 256 * j);
;                     v[k][j] = v[k][j] + g * (y[j] * rstd * gp); }
;             }
;             if (R.init || R.update) {
; #pragma unroll
;                 for (int j = 0; j < 4; ++j) __builtin_nontemporal_store(v[k][j], (f32x4*)(xrow[k] + lane * 4 + 256 * j));
;             }
;             if (R.norm_out) {
;                 float ss = 0.f;
; #pragma unroll
;                 for (int j = 0; j < 4; ++j) ss += (v[k][j][0] * v[k][j][0] + v[k][j][1] * v[k][j][1]) + (v[k][j][2] * v[k][j][2] + v[k][j][3] * v[k][j][3]);
;                 const float rstd = __builtin_amdgcn_rsqf(wave_sum(ss) * (1.0f / DM) + EPS);
;                 const float* shift = R.mod + ((size_t)(R.ln * 9 + bb) * NMOD + R.si) * DM; const float* scale = shift + DM;
;                 bf16* hr = R.H + (size_t)row * DM;
; #pragma unroll
;                 for (int j = 0; j < 4; ++j) { const f32x4 gp = *(const f32x4*)(R.gpre + lane * 4 + 256 * j), sh = *(const f32x4*)(shift + lane * 4 + 256 * j), sc = *(const f32x4*)(scale + lane * 4 + 256 * j);
;                     const f32x4 hv = (v[k][j] * rstd * gp) * (sc + 1.0f) + sh;
;                     u32x2 w; w.x = pk2(hv[0], hv[1]); w.y = pk2(hv[2], hv[3]); *(u32x2*)(hr + lane * 4 + 256 * j) = w; }
;             }
.Lr2_slow_proc:
	s_barrier
	v_add_u32_e32 v37, s93, v160
	ds_read_b128 v[64:67], v37
	ds_read_b128 v[68:71], v37 offset:1024
	ds_read_b128 v[72:75], v37 offset:2048
	ds_read_b128 v[76:79], v37 offset:3072
	ds_read_b128 v[80:83], v37 offset:4096
	ds_read_b128 v[84:87], v37 offset:5120
	ds_read_b128 v[88:91], v37 offset:6144
	ds_read_b128 v[92:95], v37 offset:7168
	v_lshlrev_b32_e32 v172, 16, v54
	v_and_b32_e32 v173, 0xffff0000, v54
	v_lshlrev_b32_e32 v174, 16, v55
	v_and_b32_e32 v175, 0xffff0000, v55
	v_pk_mul_f32 v[166:167], v[172:173], v[172:173]
	v_pk_mul_f32 v[168:169], v[174:175], v[174:175]
	v_lshlrev_b32_e32 v176, 16, v52
	v_and_b32_e32 v177, 0xffff0000, v52
	v_lshlrev_b32_e32 v178, 16, v53
	v_and_b32_e32 v179, 0xffff0000, v53
	v_pk_fma_f32 v[166:167], v[176:177], v[176:177], v[166:167]
	v_pk_fma_f32 v[168:169], v[178:179], v[178:179], v[168:169]
	v_lshlrev_b32_e32 v180, 16, v50
	v_and_b32_e32 v181, 0xffff0000, v50
	v_lshlrev_b32_e32 v182, 16, v51
	v_and_b32_e32 v183, 0xffff0000, v51
	v_pk_fma_f32 v[166:167], v[180:181], v[180:181], v[166:167]
	v_pk_fma_f32 v[168:169], v[182:183], v[182:183], v[168:169]
	v_lshlrev_b32_e32 v184, 16, v48
	v_and_b32_e32 v185, 0xffff0000, v48
	v_lshlrev_b32_e32 v186, 16, v49
	v_and_b32_e32 v187, 0xffff0000, v49
	v_pk_fma_f32 v[166:167], v[184:185], v[184:185], v[166:167]
	v_pk_fma_f32 v[168:169], v[186:187], v[186:187], v[168:169]
	v_pk_add_f32 v[166:167], v[166:167], v[168:169]
	s_nop 0
	v_add_f32_e32 v164, v166, v167
	v_mov_b32_e32 v165, v164
	s_nop 1
	v_permlane32_swap_b32_e32 v165, v164
	v_add_f32_e32 v164, v164, v165
	v_mov_b32_e32 v165, v164
	s_nop 1
	v_permlane16_swap_b32_e32 v165, v164
	v_add_f32_e32 v164, v164, v165
	s_nop 1
	v_add_f32_dpp v164, v164, v164 row_ror:8 row_mask:0xf bank_mask:0xf
	s_nop 1
	v_add_f32_dpp v164, v164, v164 row_ror:4 row_mask:0xf bank_mask:0xf
	s_nop 1
	v_add_f32_dpp v164, v164, v164 row_ror:2 row_mask:0xf bank_mask:0xf
	s_nop 1
	v_add_f32_dpp v164, v164, v164 row_ror:1 row_mask:0xf bank_mask:0xf
	s_nop 0
	v_fmamk_f32 v164, v164, 0x3a800000, v200
	v_rsq_f32_e32 v164, v164
	s_nop 0
	v_pk_mul_f32 v[172:173], v[172:173], v[164:165] op_sel_hi:[1,0]
	v_pk_mul_f32 v[174:175], v[174:175], v[164:165] op_sel_hi:[1,0]
	v_pk_mul_f32 v[172:173], v[218:219], v[172:173]
	v_pk_mul_f32 v[174:175], v[220:221], v[174:175]
	s_waitcnt lgkmcnt(7)
	v_pk_fma_f32 v[12:13], v[64:65], v[172:173], v[12:13]
	v_pk_fma_f32 v[14:15], v[66:67], v[174:175], v[14:15]
	global_store_dwordx4 v160, v[12:15], s[40:41] nt
	v_pk_mul_f32 v[176:177], v[176:177], v[164:165] op_sel_hi:[1,0]
	v_pk_mul_f32 v[178:179], v[178:179], v[164:165] op_sel_hi:[1,0]
	v_pk_mul_f32 v[176:177], v[222:223], v[176:177]
	v_pk_mul_f32 v[178:179], v[224:225], v[178:179]
	s_waitcnt lgkmcnt(6)
	v_pk_fma_f32 v[8:9], v[68:69], v[176:177], v[8:9]
	v_pk_fma_f32 v[10:11], v[70:71], v[178:179], v[10:11]
	global_store_dwordx4 v160, v[8:11], s[40:41] offset:1024 nt
	v_pk_mul_f32 v[180:181], v[180:181], v[164:165] op_sel_hi:[1,0]
	v_pk_mul_f32 v[182:183], v[182:183], v[164:165] op_sel_hi:[1,0]
	v_pk_mul_f32 v[180:181], v[226:227], v[180:181]
	v_pk_mul_f32 v[182:183], v[228:229], v[182:183]
	s_waitcnt lgkmcnt(5)
	v_pk_fma_f32 v[4:5], v[72:73], v[180:181], v[4:5]
	v_pk_fma_f32 v[6:7], v[74:75], v[182:183], v[6:7]
	global_store_dwordx4 v160, v[4:7], s[40:41] offset:2048 nt
	v_pk_mul_f32 v[184:185], v[184:185], v[164:165] op_sel_hi:[1,0]
	v_pk_mul_f32 v[186:187], v[186:187], v[164:165] op_sel_hi:[1,0]
	v_pk_mul_f32 v[184:185], v[230:231], v[184:185]
	v_pk_mul_f32 v[186:187], v[232:233], v[186:187]
	s_waitcnt lgkmcnt(4)
	v_pk_fma_f32 v[0:1], v[76:77], v[184:185], v[0:1]
	v_pk_fma_f32 v[2:3], v[78:79], v[186:187], v[2:3]
	global_store_dwordx4 v160, v[0:3], s[40:41] offset:3072 nt
	s_waitcnt lgkmcnt(0)
	ds_read_b128 v[172:175], v37 offset:8192
	ds_read_b128 v[176:179], v37 offset:9216
	ds_read_b128 v[180:183], v37 offset:10240
	ds_read_b128 v[184:187], v37 offset:11264
	ds_read_b128 v[188:191], v37 offset:12288
	ds_read_b128 v[192:195], v37 offset:13312
	ds_read_b128 v[196:199], v37 offset:14336
	ds_read_b128 v[96:99], v37 offset:15360
	ds_read_b128 v[64:67], v37 offset:16384
	ds_read_b128 v[68:71], v37 offset:17408
	ds_read_b128 v[72:75], v37 offset:18432
	ds_read_b128 v[76:79], v37 offset:19456
	v_add_co_u32_e32 v250, vcc, 0xfbc00000, v46
	v_addc_co_u32_e32 v251, vcc, -1, v47, vcc
	v_pk_mul_f32 v[166:167], v[12:13], v[12:13]
	v_pk_mul_f32 v[168:169], v[14:15], v[14:15]
	v_pk_fma_f32 v[166:167], v[8:9], v[8:9], v[166:167]
	v_pk_fma_f32 v[168:169], v[10:11], v[10:11], v[168:169]
	v_pk_fma_f32 v[166:167], v[4:5], v[4:5], v[166:167]
	v_pk_fma_f32 v[168:169], v[6:7], v[6:7], v[168:169]
	v_pk_fma_f32 v[166:167], v[0:1], v[0:1], v[166:167]
	v_pk_fma_f32 v[168:169], v[2:3], v[2:3], v[168:169]
	v_pk_add_f32 v[166:167], v[166:167], v[168:169]
	s_nop 0
	v_add_f32_e32 v164, v166, v167
	v_mov_b32_e32 v165, v164
	s_nop 1
	v_permlane32_swap_b32_e32 v165, v164
	v_add_f32_e32 v164, v164, v165
	v_mov_b32_e32 v165, v164
	s_nop 1
	v_permlane16_swap_b32_e32 v165, v164
	v_add_f32_e32 v164, v164, v165
	s_nop 1
	v_add_f32_dpp v164, v164, v164 row_ror:8 row_mask:0xf bank_mask:0xf
	s_nop 1
	v_add_f32_dpp v164, v164, v164 row_ror:4 row_mask:0xf bank_mask:0xf
	s_nop 1
	v_add_f32_dpp v164, v164, v164 row_ror:2 row_mask:0xf bank_mask:0xf
	s_nop 1
	v_add_f32_dpp v164, v164, v164 row_ror:1 row_mask:0xf bank_mask:0xf
	s_nop 0
	v_fmamk_f32 v164, v164, 0x3a800000, v200
	v_rsq_f32_e32 v164, v164
	s_nop 0
	v_pk_mul_f32 v[12:13], v[12:13], v[164:165] op_sel_hi:[1,0]
	v_pk_mul_f32 v[14:15], v[14:15], v[164:165] op_sel_hi:[1,0]
	v_pk_mul_f32 v[12:13], v[234:235], v[12:13]
	v_pk_mul_f32 v[14:15], v[236:237], v[14:15]
	s_waitcnt lgkmcnt(11)
; __device__ __forceinline__ unsigned pk2(float lo, float hi) { return pg8::cvt_pk_bf16(lo, hi); }
;     __device__ __forceinline__ void init(int N, int G, int c, int latent_only) { lat = latent_only; b.init(latent_only ? NB * SEQ : M, N, G, c); }
;     __device__ __forceinline__ void init(int c_, unsigned* cnt_) { lat.init(NB * SEQ, FF2, 1, 0); c = c_; cnt = cnt_; }
; __device__ __forceinline__ void row_pass(const RowPass& R, int gw, int ngw, int lane) {
;     ...
;     for (int row0 = gw; row0 < M; row0 += NR * ngw) {
;         f32x4 v[NR][4]; u32x2 yw[NR][4]; bool act[NR]; float* xrow[NR]; int bbs[NR];
; #pragma unroll
;         for (int k = 0; k < NR; ++k) {
;             const int row = row0 + k * ngw;
;             const int rowc = row < M ? row : row0;
;             const int b = rowc / RPB, i = rowc - b * RPB; const bool isctx = i < CTXL;
;             act[k] = (row < M) && !(isctx && R.skip_ctx);
;             bbs[k] = isctx ? 8 : b;
;             xrow[k] = isctx ? R.xc + ((size_t)b * CTXL + i) * DM : R.out + ((size_t)b * SEQ + (i - CTXL)) * DM;
;             const float* src = R.init ? (isctx ? R.ctx_in + ((size_t)b * CTXL + i) * DM : R.x_in + ((size_t)b * SEQ + (i - CTXL)) * DM) : xrow[k];
;             if (act[k]) {
; #pragma unroll
;                 for (int j = 0; j < 4; ++j) v[k][j] = __builtin_nontemporal_load((const f32x4*)(src + lane * 4 + 256 * j));
;                 if (R.update) { const bf16* yr = R.Y + (size_t)rowc * DM;
; #pragma unroll
;                     for (int j = 0; j < 4; ++j) yw[k][j] = __builtin_nontemporal_load((const u32x2*)(yr + lane * 4 + 256 * j)); }
;             }
;     ...
;                 const float rstd = __builtin_amdgcn_rsqf(wave_sum(ss) * (1.0f / DM) + EPS);
;                 const float* shift = R.mod + ((size_t)(R.ln * 9 + bb) * NMOD + R.si) * DM; const float* scale = shift + DM;
;                 bf16* hr = R.H + (size_t)row * DM;
; #pragma unroll
;                 for (int j = 0; j < 4; ++j) { const f32x4 gp = *(const f32x4*)(R.gpre + lane * 4 + 256 * j), sh = *(const f32x4*)(shift + lane * 4 + 256 * j), sc = *(const f32x4*)(scale + lane * 4 + 256 * j);
;                     const f32x4 hv = (v[k][j] * rstd * gp) * (sc + 1.0f) + sh;
;                     u32x2 w; w.x = pk2(hv[0], hv[1]); w.y = pk2(hv[2], hv[3]); *(u32x2*)(hr + lane * 4 + 256 * j) = w; }
;             }
	v_pk_add_f32 v[172:173], v[172:173], 1.0 op_sel_hi:[1,0]
	v_pk_add_f32 v[174:175], v[174:175], 1.0 op_sel_hi:[1,0]
	v_pk_fma_f32 v[12:13], v[172:173], v[12:13], v[80:81]
	v_pk_fma_f32 v[14:15], v[174:175], v[14:15], v[82:83]
	v_cvt_pk_bf16_f32 v12, v12, v13
	v_cvt_pk_bf16_f32 v13, v14, v15
	global_store_dwordx2 v[250:251], v[12:13], off offset:-1536
	ds_read_b128 v[80:83], v37 offset:20480
	v_pk_mul_f32 v[8:9], v[8:9], v[164:165] op_sel_hi:[1,0]
	v_pk_mul_f32 v[10:11], v[10:11], v[164:165] op_sel_hi:[1,0]
	v_pk_mul_f32 v[8:9], v[238:239], v[8:9]
	v_pk_mul_f32 v[10:11], v[240:241], v[10:11]
	s_waitcnt lgkmcnt(11)
	v_pk_add_f32 v[176:177], v[176:177], 1.0 op_sel_hi:[1,0]
	v_pk_add_f32 v[178:179], v[178:179], 1.0 op_sel_hi:[1,0]
	v_pk_fma_f32 v[8:9], v[176:177], v[8:9], v[84:85]
	v_pk_fma_f32 v[10:11], v[178:179], v[10:11], v[86:87]
	v_cvt_pk_bf16_f32 v8, v8, v9
	v_cvt_pk_bf16_f32 v9, v10, v11
	global_store_dwordx2 v[250:251], v[8:9], off offset:-1024
	ds_read_b128 v[84:87], v37 offset:21504
	v_pk_mul_f32 v[4:5], v[4:5], v[164:165] op_sel_hi:[1,0]
	v_pk_mul_f32 v[6:7], v[6:7], v[164:165] op_sel_hi:[1,0]
	v_pk_mul_f32 v[4:5], v[242:243], v[4:5]
	v_pk_mul_f32 v[6:7], v[244:245], v[6:7]
	s_waitcnt lgkmcnt(11)
	v_pk_add_f32 v[180:181], v[180:181], 1.0 op_sel_hi:[1,0]
	v_pk_add_f32 v[182:183], v[182:183], 1.0 op_sel_hi:[1,0]
	v_pk_fma_f32 v[4:5], v[180:181], v[4:5], v[88:89]
	v_pk_fma_f32 v[6:7], v[182:183], v[6:7], v[90:91]
	v_cvt_pk_bf16_f32 v4, v4, v5
	v_cvt_pk_bf16_f32 v5, v6, v7
	global_store_dwordx2 v[250:251], v[4:5], off offset:-512
	ds_read_b128 v[88:91], v37 offset:22528
	v_pk_mul_f32 v[0:1], v[0:1], v[164:165] op_sel_hi:[1,0]
	v_pk_mul_f32 v[2:3], v[2:3], v[164:165] op_sel_hi:[1,0]
	v_pk_mul_f32 v[0:1], v[246:247], v[0:1]
	v_pk_mul_f32 v[2:3], v[248:249], v[2:3]
	s_waitcnt lgkmcnt(11)
	v_pk_add_f32 v[184:185], v[184:185], 1.0 op_sel_hi:[1,0]
	v_pk_add_f32 v[186:187], v[186:187], 1.0 op_sel_hi:[1,0]
	v_pk_fma_f32 v[0:1], v[184:185], v[0:1], v[92:93]
	v_pk_fma_f32 v[2:3], v[186:187], v[2:3], v[94:95]
	v_cvt_pk_bf16_f32 v0, v0, v1
	v_cvt_pk_bf16_f32 v1, v2, v3
	global_store_dwordx2 v[250:251], v[0:1], off
	ds_read_b128 v[92:95], v37 offset:23552
	s_waitcnt vmcnt(8)
	s_mov_b32 s99, 0
	s_add_i32 s72, s13, s48
	s_cmp_gt_i32 s72, 0x87ff
	s_cbranch_scc1 .Lr2_slow_nopf
	s_add_i32 s8, s44, s72
	s_cmp_lt_i32 s8, 0x8800
	s_cbranch_scc0 .Lr2_slow_nopf
	s_mov_b32 s41, s72
	s_mul_hi_i32 s6, s41, 0x78787879
	s_lshr_b32 s7, s6, 31
	s_ashr_i32 s6, s6, 11
	s_add_i32 s6, s6, s7
	s_mul_i32 s7, s6, 0xffffef00
	s_add_i32 s7, s41, s7
	s_cmpk_gt_i32 s7, 0xff
	s_cselect_b64 s[50:51], -1, 0
	s_mul_hi_i32 s9, s8, 0x78787879
	s_lshr_b32 s25, s9, 31
	s_ashr_i32 s9, s9, 11
	s_add_i32 s9, s9, s25
	s_mul_i32 s25, s9, 0xffffef00
	s_add_i32 s25, s8, s25
	s_cmpk_gt_i32 s25, 0xff
	s_cselect_b64 s[52:53], -1, 0
	s_and_b64 s[46:47], s[50:51], s[52:53]
	s_or_b64 s[46:47], s[46:47], s[62:63]
	s_cmp_lg_u64 s[46:47], 0
	s_cbranch_scc0 .Lr2_slow_nopf
	s_add_i32 s72, s7, 0xffffff00
	s_cmp_lg_u64 s[50:51], 0
	s_cselect_b32 s27, s4, s49
	s_cselect_b32 s32, s5, s55
	s_cselect_b32 s37, 24, 20
	s_cselect_b32 s72, s72, s7
	s_cselect_b32 s85, s6, 8
	s_mov_b32 s40, s6
	s_mov_b32 s41, 0
	s_lshl_b64 s[40:41], s[40:41], s37
	s_add_u32 s40, s27, s40
	s_addc_u32 s41, s32, s41
	s_lshl_b32 s72, s72, 12
	s_add_u32 s40, s40, s72
	s_addc_u32 s41, s41, 0
	s_add_i32 s27, s85, s3
	s_mul_hi_i32 s32, s27, 0x6000
	s_mulk_i32 s27, 0x6000
	s_add_u32 s66, s34, s27
	s_addc_u32 s67, s35, s32
	s_add_u32 s66, s66, 0x2000
	s_addc_u32 s67, s67, 0
	s_add_i32 s27, s85, s3
	s_mul_hi_i32 s32, s27, 0x6000
	s_mulk_i32 s27, 0x6000
	s_add_u32 s38, s34, s27
	s_addc_u32 s39, s35, s32
	s_add_u32 s38, s38, 0x3000
	s_addc_u32 s39, s39, 0
	s_add_u32 s46, s38, 0x1000
	s_addc_u32 s47, s39, 0
	s_mov_b64 s[6:7], s[52:53]
	s_cmp_lg_u64 s[6:7], 0
	s_cselect_b32 s85, s9, 8
	s_add_i32 s27, s85, s3
	s_mul_hi_i32 s32, s27, 0x6000
	s_mulk_i32 s27, 0x6000
	s_add_u32 s10, s34, s27
	s_addc_u32 s11, s35, s32
	s_add_u32 s10, s10, 0x2000
	s_addc_u32 s11, s11, 0
	s_add_i32 s27, s85, s3
	s_mul_hi_i32 s32, s27, 0x6000
	s_mulk_i32 s27, 0x6000
	s_add_u32 s50, s34, s27
	s_addc_u32 s51, s35, s32
	s_add_u32 s50, s50, 0x3000
	s_addc_u32 s51, s51, 0
	s_add_u32 s52, s50, 0x1000
	s_addc_u32 s53, s51, 0
	s_xor_b32 s25, s93, 0x6000
	v_lshl_add_u64 v[250:251], v[46:47], 0, s[74:75]
	global_load_dwordx4 v[12:15], v160, s[40:41] nt
	global_load_dwordx4 v[8:11], v160, s[40:41] offset:1024 nt
	global_load_dwordx4 v[4:7], v160, s[40:41] offset:2048 nt
	global_load_dwordx4 v[0:3], v160, s[40:41] offset:3072 nt
	global_load_dwordx2 v[54:55], v[250:251], off offset:-1536 nt
	global_load_dwordx2 v[52:53], v[250:251], off offset:-1024 nt
	global_load_dwordx2 v[50:51], v[250:251], off offset:-512 nt
	global_load_dwordx2 v[48:49], v[250:251], off nt
	s_and_b32 s72, s13, 7
	s_and_b32 s85, s72, 3
	s_lshl_b32 s85, s85, 10
	s_lshl_b32 s37, s72, 10
	s_add_i32 s37, s37, s25
	s_cmp_lt_u32 s72, 4
	s_cselect_b32 s6, s66, s38
	s_cselect_b32 s7, s67, s39
	s_cselect_b32 s8, s46, s10
	s_cselect_b32 s9, s47, s11
	s_cselect_b32 s26, s50, s52
	s_cselect_b32 s27, s51, s53
	s_add_u32 s6, s6, s85
	s_addc_u32 s7, s7, 0
	s_add_u32 s8, s8, s85
	s_addc_u32 s9, s9, 0
	s_add_u32 s26, s26, s85
	s_addc_u32 s27, s27, 0
	s_mov_b32 m0, s37
	s_nop 0
	global_load_lds_dwordx4 v160, s[6:7]
	s_add_i32 s37, s37, 0x2000
	s_mov_b32 m0, s37
	s_nop 0
	global_load_lds_dwordx4 v160, s[8:9]
	s_add_i32 s37, s37, 0x2000
	s_mov_b32 m0, s37
	s_nop 0
	global_load_lds_dwordx4 v160, s[26:27]
	s_mov_b32 s99, 1
; __device__ __forceinline__ unsigned pk2(float lo, float hi) { return pg8::cvt_pk_bf16(lo, hi); }
; __device__ __forceinline__ float bflo(unsigned w) { return __uint_as_float(w << 16); }
; __device__ __forceinline__ float bfhi(unsigned w) { return __uint_as_float(w & 0xffff0000u); }
; __device__ __forceinline__ void row_pass(const RowPass& R, int gw, int ngw, int lane) {
;     ...
;             if (R.update) {
;                 f32x4 y[4]; float ss = 0.f;
; #pragma unroll
;                 for (int j = 0; j < 4; ++j) { const u32x2 w = yw[k][j]; y[j] = (f32x4){bflo(w.x), bfhi(w.x), bflo(w.y), bfhi(w.y)};
;                     ss += (y[j][0] * y[j][0] + y[j][1] * y[j][1]) + (y[j][2] * y[j][2] + y[j][3] * y[j][3]); }
;                 const float rstd = __builtin_amdgcn_rsqf(wave_sum(ss) * (1.0f / DM) + EPS);
;                 const float* gate = R.mod + ((size_t)(R.lg * 9 + bb) * NMOD + R.gi) * DM;
; #pragma unroll
;                 for (int j = 0; j < 4; ++j) { const f32x4 g = *(const f32x4*)(gate + lane * 4 + 256 * j), gp = *(const f32x4*)(R.gpost + lane * 4 + 256 * j);
;                     v[k][j] = v[k][j] + g * (y[j] * rstd * gp); }
;             }
;             if (R.init || R.update) {
; #pragma unroll
;                 for (int j = 0; j < 4; ++j) __builtin_nontemporal_store(v[k][j], (f32x4*)(xrow[k] + lane * 4 + 256 * j));
;             }
;             if (R.norm_out) {
;                 float ss = 0.f;
; #pragma unroll
;                 for (int j = 0; j < 4; ++j) ss += (v[k][j][0] * v[k][j][0] + v[k][j][1] * v[k][j][1]) + (v[k][j][2] * v[k][j][2] + v[k][j][3] * v[k][j][3]);
;                 const float rstd = __builtin_amdgcn_rsqf(wave_sum(ss) * (1.0f / DM) + EPS);
;                 const float* shift = R.mod + ((size_t)(R.ln * 9 + bb) * NMOD + R.si) * DM; const float* scale = shift + DM;
;                 bf16* hr = R.H + (size_t)row * DM;
; #pragma unroll
;                 for (int j = 0; j < 4; ++j) { const f32x4 gp = *(const f32x4*)(R.gpre + lane * 4 + 256 * j), sh = *(const f32x4*)(shift + lane * 4 + 256 * j), sc = *(const f32x4*)(scale + lane * 4 + 256 * j);
;                     const f32x4 hv = (v[k][j] * rstd * gp) * (sc + 1.0f) + sh;
;                     u32x2 w; w.x = pk2(hv[0], hv[1]); w.y = pk2(hv[2], hv[3]); *(u32x2*)(hr + lane * 4 + 256 * j) = w; }
;             }
.Lr2_slow_nopf:
	v_lshlrev_b32_e32 v172, 16, v62
	v_and_b32_e32 v173, 0xffff0000, v62
	v_lshlrev_b32_e32 v174, 16, v63
	v_and_b32_e32 v175, 0xffff0000, v63
	v_pk_mul_f32 v[166:167], v[172:173], v[172:173]
	v_pk_mul_f32 v[168:169], v[174:175], v[174:175]
	v_lshlrev_b32_e32 v176, 16, v60
	v_and_b32_e32 v177, 0xffff0000, v60
	v_lshlrev_b32_e32 v178, 16, v61
	v_and_b32_e32 v179, 0xffff0000, v61
	v_pk_fma_f32 v[166:167], v[176:177], v[176:177], v[166:167]
	v_pk_fma_f32 v[168:169], v[178:179], v[178:179], v[168:169]
	v_lshlrev_b32_e32 v180, 16, v58
	v_and_b32_e32 v181, 0xffff0000, v58
	v_lshlrev_b32_e32 v182, 16, v59
	v_and_b32_e32 v183, 0xffff0000, v59
	v_pk_fma_f32 v[166:167], v[180:181], v[180:181], v[166:167]
	v_pk_fma_f32 v[168:169], v[182:183], v[182:183], v[168:169]
	v_lshlrev_b32_e32 v184, 16, v56
	v_and_b32_e32 v185, 0xffff0000, v56
	v_lshlrev_b32_e32 v186, 16, v57
	v_and_b32_e32 v187, 0xffff0000, v57
	v_pk_fma_f32 v[166:167], v[184:185], v[184:185], v[166:167]
	v_pk_fma_f32 v[168:169], v[186:187], v[186:187], v[168:169]
	v_pk_add_f32 v[166:167], v[166:167], v[168:169]
	s_nop 0
	v_add_f32_e32 v164, v166, v167
	v_mov_b32_e32 v165, v164
	s_nop 1
	v_permlane32_swap_b32_e32 v165, v164
	v_add_f32_e32 v164, v164, v165
	v_mov_b32_e32 v165, v164
	s_nop 1
	v_permlane16_swap_b32_e32 v165, v164
	v_add_f32_e32 v164, v164, v165
	s_nop 1
	v_add_f32_dpp v164, v164, v164 row_ror:8 row_mask:0xf bank_mask:0xf
	s_nop 1
	v_add_f32_dpp v164, v164, v164 row_ror:4 row_mask:0xf bank_mask:0xf
	s_nop 1
	v_add_f32_dpp v164, v164, v164 row_ror:2 row_mask:0xf bank_mask:0xf
	s_nop 1
	v_add_f32_dpp v164, v164, v164 row_ror:1 row_mask:0xf bank_mask:0xf
	s_nop 0
	v_fmamk_f32 v164, v164, 0x3a800000, v200
	v_rsq_f32_e32 v164, v164
	s_nop 0
	v_pk_mul_f32 v[172:173], v[172:173], v[164:165] op_sel_hi:[1,0]
	v_pk_mul_f32 v[174:175], v[174:175], v[164:165] op_sel_hi:[1,0]
	v_pk_mul_f32 v[172:173], v[218:219], v[172:173]
	v_pk_mul_f32 v[174:175], v[220:221], v[174:175]
	s_waitcnt lgkmcnt(11)
	v_pk_fma_f32 v[16:17], v[188:189], v[172:173], v[16:17]
	v_pk_fma_f32 v[18:19], v[190:191], v[174:175], v[18:19]
	global_store_dwordx4 v160, v[16:19], s[64:65] nt
	v_pk_mul_f32 v[176:177], v[176:177], v[164:165] op_sel_hi:[1,0]
	v_pk_mul_f32 v[178:179], v[178:179], v[164:165] op_sel_hi:[1,0]
	v_pk_mul_f32 v[176:177], v[222:223], v[176:177]
	v_pk_mul_f32 v[178:179], v[224:225], v[178:179]
	s_waitcnt lgkmcnt(10)
	v_pk_fma_f32 v[20:21], v[192:193], v[176:177], v[20:21]
	v_pk_fma_f32 v[22:23], v[194:195], v[178:179], v[22:23]
	global_store_dwordx4 v160, v[20:23], s[64:65] offset:1024 nt
	v_pk_mul_f32 v[180:181], v[180:181], v[164:165] op_sel_hi:[1,0]
	v_pk_mul_f32 v[182:183], v[182:183], v[164:165] op_sel_hi:[1,0]
	v_pk_mul_f32 v[180:181], v[226:227], v[180:181]
	v_pk_mul_f32 v[182:183], v[228:229], v[182:183]
	s_waitcnt lgkmcnt(9)
	v_pk_fma_f32 v[24:25], v[196:197], v[180:181], v[24:25]
	v_pk_fma_f32 v[26:27], v[198:199], v[182:183], v[26:27]
	global_store_dwordx4 v160, v[24:27], s[64:65] offset:2048 nt
	v_pk_mul_f32 v[184:185], v[184:185], v[164:165] op_sel_hi:[1,0]
	v_pk_mul_f32 v[186:187], v[186:187], v[164:165] op_sel_hi:[1,0]
	v_pk_mul_f32 v[184:185], v[230:231], v[184:185]
	v_pk_mul_f32 v[186:187], v[232:233], v[186:187]
	s_waitcnt lgkmcnt(8)
	v_pk_fma_f32 v[28:29], v[96:97], v[184:185], v[28:29]
	v_pk_fma_f32 v[30:31], v[98:99], v[186:187], v[30:31]
	global_store_dwordx4 v160, v[28:31], s[64:65] offset:3072 nt
	v_pk_mul_f32 v[166:167], v[16:17], v[16:17]
	v_pk_mul_f32 v[168:169], v[18:19], v[18:19]
	v_pk_fma_f32 v[166:167], v[20:21], v[20:21], v[166:167]
	v_pk_fma_f32 v[168:169], v[22:23], v[22:23], v[168:169]
	v_pk_fma_f32 v[166:167], v[24:25], v[24:25], v[166:167]
	v_pk_fma_f32 v[168:169], v[26:27], v[26:27], v[168:169]
	v_pk_fma_f32 v[166:167], v[28:29], v[28:29], v[166:167]
	v_pk_fma_f32 v[168:169], v[30:31], v[30:31], v[168:169]
	v_pk_add_f32 v[166:167], v[166:167], v[168:169]
	s_nop 0
	v_add_f32_e32 v164, v166, v167
	v_mov_b32_e32 v165, v164
	s_nop 1
	v_permlane32_swap_b32_e32 v165, v164
	v_add_f32_e32 v164, v164, v165
	v_mov_b32_e32 v165, v164
	s_nop 1
	v_permlane16_swap_b32_e32 v165, v164
	v_add_f32_e32 v164, v164, v165
	s_nop 1
	v_add_f32_dpp v164, v164, v164 row_ror:8 row_mask:0xf bank_mask:0xf
	s_nop 1
	v_add_f32_dpp v164, v164, v164 row_ror:4 row_mask:0xf bank_mask:0xf
	s_nop 1
	v_add_f32_dpp v164, v164, v164 row_ror:2 row_mask:0xf bank_mask:0xf
	s_nop 1
	v_add_f32_dpp v164, v164, v164 row_ror:1 row_mask:0xf bank_mask:0xf
	s_nop 0
	v_fmamk_f32 v164, v164, 0x3a800000, v200
	v_rsq_f32_e32 v164, v164
	s_nop 0
	v_pk_mul_f32 v[16:17], v[16:17], v[164:165] op_sel_hi:[1,0]
	v_pk_mul_f32 v[18:19], v[18:19], v[164:165] op_sel_hi:[1,0]
	v_pk_mul_f32 v[16:17], v[234:235], v[16:17]
	v_pk_mul_f32 v[18:19], v[236:237], v[18:19]
	s_waitcnt lgkmcnt(3)
	v_pk_add_f32 v[80:81], v[80:81], 1.0 op_sel_hi:[1,0]
	v_pk_add_f32 v[82:83], v[82:83], 1.0 op_sel_hi:[1,0]
	v_pk_fma_f32 v[16:17], v[80:81], v[16:17], v[64:65]
	v_pk_fma_f32 v[18:19], v[82:83], v[18:19], v[66:67]
	v_cvt_pk_bf16_f32 v16, v16, v17
	v_cvt_pk_bf16_f32 v17, v18, v19
	global_store_dwordx2 v[252:253], v[16:17], off
	v_pk_mul_f32 v[20:21], v[20:21], v[164:165] op_sel_hi:[1,0]
	v_pk_mul_f32 v[22:23], v[22:23], v[164:165] op_sel_hi:[1,0]
	v_pk_mul_f32 v[20:21], v[238:239], v[20:21]
	v_pk_mul_f32 v[22:23], v[240:241], v[22:23]
	s_waitcnt lgkmcnt(2)
	v_pk_add_f32 v[84:85], v[84:85], 1.0 op_sel_hi:[1,0]
	v_pk_add_f32 v[86:87], v[86:87], 1.0 op_sel_hi:[1,0]
	v_pk_fma_f32 v[20:21], v[84:85], v[20:21], v[68:69]
	v_pk_fma_f32 v[22:23], v[86:87], v[22:23], v[70:71]
	v_cvt_pk_bf16_f32 v20, v20, v21
	v_cvt_pk_bf16_f32 v21, v22, v23
	global_store_dwordx2 v[252:253], v[20:21], off offset:512
	v_pk_mul_f32 v[24:25], v[24:25], v[164:165] op_sel_hi:[1,0]
	v_pk_mul_f32 v[26:27], v[26:27], v[164:165] op_sel_hi:[1,0]
	v_pk_mul_f32 v[24:25], v[242:243], v[24:25]
	v_pk_mul_f32 v[26:27], v[244:245], v[26:27]
	s_waitcnt lgkmcnt(1)
	v_pk_add_f32 v[88:89], v[88:89], 1.0 op_sel_hi:[1,0]
	v_pk_add_f32 v[90:91], v[90:91], 1.0 op_sel_hi:[1,0]
	v_pk_fma_f32 v[24:25], v[88:89], v[24:25], v[72:73]
	v_pk_fma_f32 v[26:27], v[90:91], v[26:27], v[74:75]
	v_cvt_pk_bf16_f32 v24, v24, v25
	v_cvt_pk_bf16_f32 v25, v26, v27
	global_store_dwordx2 v[252:253], v[24:25], off offset:1024
	v_pk_mul_f32 v[28:29], v[28:29], v[164:165] op_sel_hi:[1,0]
	v_pk_mul_f32 v[30:31], v[30:31], v[164:165] op_sel_hi:[1,0]
	v_pk_mul_f32 v[28:29], v[246:247], v[28:29]
	v_pk_mul_f32 v[30:31], v[248:249], v[30:31]
	s_waitcnt lgkmcnt(0)
	v_pk_add_f32 v[92:93], v[92:93], 1.0 op_sel_hi:[1,0]
	v_pk_add_f32 v[94:95], v[94:95], 1.0 op_sel_hi:[1,0]
	v_pk_fma_f32 v[28:29], v[92:93], v[28:29], v[76:77]
	v_pk_fma_f32 v[30:31], v[94:95], v[30:31], v[78:79]
	v_cvt_pk_bf16_f32 v28, v28, v29
	v_cvt_pk_bf16_f32 v29, v30, v31
	global_store_dwordx2 v[252:253], v[28:29], off offset:1536
	s_xor_b32 s93, s93, 0x6000
	s_branch .LBB0_131

; __device__ __forceinline__ unsigned pk2(float lo, float hi) { return pg8::cvt_pk_bf16(lo, hi); }
; __device__ __forceinline__ float bflo(unsigned w) { return __uint_as_float(w << 16); }
; __device__ __forceinline__ float bfhi(unsigned w) { return __uint_as_float(w & 0xffff0000u); }
; __device__ __forceinline__ void row_pass(const RowPass& R, int gw, int ngw, int lane) {
;     ...
;             if (R.update) {
;                 f32x4 y[4]; float ss = 0.f;
; #pragma unroll
;                 for (int j = 0; j < 4; ++j) { const u32x2 w = yw[k][j]; y[j] = (f32x4){bflo(w.x), bfhi(w.x), bflo(w.y), bfhi(w.y)};
;                     ss += (y[j][0] * y[j][0] + y[j][1] * y[j][1]) + (y[j][2] * y[j][2] + y[j][3] * y[j][3]); }
;                 const float rstd = __builtin_amdgcn_rsqf(wave_sum(ss) * (1.0f / DM) + EPS);
;                 const float* gate = R.mod + ((size_t)(R.lg * 9 + bb) * NMOD + R.gi) * DM;
; #pragma unroll
;                 for (int j = 0; j < 4; ++j) { const f32x4 g = *(const f32x4*)(gate + lane * 4 + 256 * j), gp = *(const f32x4*)(R.gpost + lane * 4 + 256 * j);
;                     v[k][j] = v[k][j] + g * (y[j] * rstd * gp); }
;             }
;             if (R.init || R.update) {
; #pragma unroll
;                 for (int j = 0; j < 4; ++j) __builtin_nontemporal_store(v[k][j], (f32x4*)(xrow[k] + lane * 4 + 256 * j));
;             }
;             if (R.norm_out) {
;                 float ss = 0.f;
; #pragma unroll
;                 for (int j = 0; j < 4; ++j) ss += (v[k][j][0] * v[k][j][0] + v[k][j][1] * v[k][j][1]) + (v[k][j][2] * v[k][j][2] + v[k][j][3] * v[k][j][3]);
;                 const float rstd = __builtin_amdgcn_rsqf(wave_sum(ss) * (1.0f / DM) + EPS);
;                 const float* shift = R.mod + ((size_t)(R.ln * 9 + bb) * NMOD + R.si) * DM; const float* scale = shift + DM;
;                 bf16* hr = R.H + (size_t)row * DM;
; #pragma unroll
;                 for (int j = 0; j < 4; ++j) { const f32x4 gp = *(const f32x4*)(R.gpre + lane * 4 + 256 * j), sh = *(const f32x4*)(shift + lane * 4 + 256 * j), sc = *(const f32x4*)(scale + lane * 4 + 256 * j);
;                     const f32x4 hv = (v[k][j] * rstd * gp) * (sc + 1.0f) + sh;
;                     u32x2 w; w.x = pk2(hv[0], hv[1]); w.y = pk2(hv[2], hv[3]); *(u32x2*)(hr + lane * 4 + 256 * j) = w; }
;             }
.Lr3_slow_proc:
	s_barrier
	v_add_u32_e32 v37, s93, v160
	ds_read_b128 v[64:67], v37
	ds_read_b128 v[68:71], v37 offset:1024
	ds_read_b128 v[72:75], v37 offset:2048
	ds_read_b128 v[76:79], v37 offset:3072
	ds_read_b128 v[80:83], v37 offset:4096
	ds_read_b128 v[84:87], v37 offset:5120
	ds_read_b128 v[88:91], v37 offset:6144
	ds_read_b128 v[92:95], v37 offset:7168
	v_lshlrev_b32_e32 v172, 16, v54
	v_and_b32_e32 v173, 0xffff0000, v54
	v_lshlrev_b32_e32 v174, 16, v55
	v_and_b32_e32 v175, 0xffff0000, v55
	v_pk_mul_f32 v[166:167], v[172:173], v[172:173]
	v_pk_mul_f32 v[168:169], v[174:175], v[174:175]
	v_lshlrev_b32_e32 v176, 16, v52
	v_and_b32_e32 v177, 0xffff0000, v52
	v_lshlrev_b32_e32 v178, 16, v53
	v_and_b32_e32 v179, 0xffff0000, v53
	v_pk_fma_f32 v[166:167], v[176:177], v[176:177], v[166:167]
	v_pk_fma_f32 v[168:169], v[178:179], v[178:179], v[168:169]
	v_lshlrev_b32_e32 v180, 16, v50
	v_and_b32_e32 v181, 0xffff0000, v50
	v_lshlrev_b32_e32 v182, 16, v51
	v_and_b32_e32 v183, 0xffff0000, v51
	v_pk_fma_f32 v[166:167], v[180:181], v[180:181], v[166:167]
	v_pk_fma_f32 v[168:169], v[182:183], v[182:183], v[168:169]
	v_lshlrev_b32_e32 v184, 16, v48
	v_and_b32_e32 v185, 0xffff0000, v48
	v_lshlrev_b32_e32 v186, 16, v49
	v_and_b32_e32 v187, 0xffff0000, v49
	v_pk_fma_f32 v[166:167], v[184:185], v[184:185], v[166:167]
	v_pk_fma_f32 v[168:169], v[186:187], v[186:187], v[168:169]
	v_pk_add_f32 v[166:167], v[166:167], v[168:169]
	s_nop 0
	v_add_f32_e32 v164, v166, v167
	v_mov_b32_e32 v165, v164
	s_nop 1
	v_permlane32_swap_b32_e32 v165, v164
	v_add_f32_e32 v164, v164, v165
	v_mov_b32_e32 v165, v164
	s_nop 1
	v_permlane16_swap_b32_e32 v165, v164
	v_add_f32_e32 v164, v164, v165
	s_nop 1
	v_add_f32_dpp v164, v164, v164 row_ror:8 row_mask:0xf bank_mask:0xf
	s_nop 1
	v_add_f32_dpp v164, v164, v164 row_ror:4 row_mask:0xf bank_mask:0xf
	s_nop 1
	v_add_f32_dpp v164, v164, v164 row_ror:2 row_mask:0xf bank_mask:0xf
	s_nop 1
	v_add_f32_dpp v164, v164, v164 row_ror:1 row_mask:0xf bank_mask:0xf
	s_nop 0
	v_fmamk_f32 v164, v164, 0x3a800000, v200
	v_rsq_f32_e32 v164, v164
	s_nop 0
	v_pk_mul_f32 v[172:173], v[172:173], v[164:165] op_sel_hi:[1,0]
	v_pk_mul_f32 v[174:175], v[174:175], v[164:165] op_sel_hi:[1,0]
	v_pk_mul_f32 v[172:173], v[218:219], v[172:173]
	v_pk_mul_f32 v[174:175], v[220:221], v[174:175]
	s_waitcnt lgkmcnt(7)
	v_pk_fma_f32 v[12:13], v[64:65], v[172:173], v[12:13]
	v_pk_fma_f32 v[14:15], v[66:67], v[174:175], v[14:15]
	global_store_dwordx4 v160, v[12:15], s[40:41] nt
	v_pk_mul_f32 v[176:177], v[176:177], v[164:165] op_sel_hi:[1,0]
	v_pk_mul_f32 v[178:179], v[178:179], v[164:165] op_sel_hi:[1,0]
	v_pk_mul_f32 v[176:177], v[222:223], v[176:177]
	v_pk_mul_f32 v[178:179], v[224:225], v[178:179]
	s_waitcnt lgkmcnt(6)
	v_pk_fma_f32 v[8:9], v[68:69], v[176:177], v[8:9]
	v_pk_fma_f32 v[10:11], v[70:71], v[178:179], v[10:11]
	global_store_dwordx4 v160, v[8:11], s[40:41] offset:1024 nt
	v_pk_mul_f32 v[180:181], v[180:181], v[164:165] op_sel_hi:[1,0]
	v_pk_mul_f32 v[182:183], v[182:183], v[164:165] op_sel_hi:[1,0]
	v_pk_mul_f32 v[180:181], v[226:227], v[180:181]
	v_pk_mul_f32 v[182:183], v[228:229], v[182:183]
	s_waitcnt lgkmcnt(5)
	v_pk_fma_f32 v[4:5], v[72:73], v[180:181], v[4:5]
	v_pk_fma_f32 v[6:7], v[74:75], v[182:183], v[6:7]
	global_store_dwordx4 v160, v[4:7], s[40:41] offset:2048 nt
	v_pk_mul_f32 v[184:185], v[184:185], v[164:165] op_sel_hi:[1,0]
	v_pk_mul_f32 v[186:187], v[186:187], v[164:165] op_sel_hi:[1,0]
	v_pk_mul_f32 v[184:185], v[230:231], v[184:185]
	v_pk_mul_f32 v[186:187], v[232:233], v[186:187]
	s_waitcnt lgkmcnt(4)
	v_pk_fma_f32 v[0:1], v[76:77], v[184:185], v[0:1]
	v_pk_fma_f32 v[2:3], v[78:79], v[186:187], v[2:3]
	global_store_dwordx4 v160, v[0:3], s[40:41] offset:3072 nt
	s_waitcnt lgkmcnt(0)
	ds_read_b128 v[172:175], v37 offset:8192
	ds_read_b128 v[176:179], v37 offset:9216
	ds_read_b128 v[180:183], v37 offset:10240
	ds_read_b128 v[184:187], v37 offset:11264
	ds_read_b128 v[188:191], v37 offset:12288
	ds_read_b128 v[192:195], v37 offset:13312
	ds_read_b128 v[196:199], v37 offset:14336
	ds_read_b128 v[96:99], v37 offset:15360
	ds_read_b128 v[64:67], v37 offset:16384
	ds_read_b128 v[68:71], v37 offset:17408
	ds_read_b128 v[72:75], v37 offset:18432
	ds_read_b128 v[76:79], v37 offset:19456
	v_add_co_u32_e32 v250, vcc, 0xfbc00000, v46
	v_addc_co_u32_e32 v251, vcc, -1, v47, vcc
	v_pk_mul_f32 v[166:167], v[12:13], v[12:13]
	v_pk_mul_f32 v[168:169], v[14:15], v[14:15]
	v_pk_fma_f32 v[166:167], v[8:9], v[8:9], v[166:167]
	v_pk_fma_f32 v[168:169], v[10:11], v[10:11], v[168:169]
	v_pk_fma_f32 v[166:167], v[4:5], v[4:5], v[166:167]
	v_pk_fma_f32 v[168:169], v[6:7], v[6:7], v[168:169]
	v_pk_fma_f32 v[166:167], v[0:1], v[0:1], v[166:167]
	v_pk_fma_f32 v[168:169], v[2:3], v[2:3], v[168:169]
	v_pk_add_f32 v[166:167], v[166:167], v[168:169]
	s_nop 0
	v_add_f32_e32 v164, v166, v167
	v_mov_b32_e32 v165, v164
	s_nop 1
	v_permlane32_swap_b32_e32 v165, v164
	v_add_f32_e32 v164, v164, v165
	v_mov_b32_e32 v165, v164
	s_nop 1
	v_permlane16_swap_b32_e32 v165, v164
	v_add_f32_e32 v164, v164, v165
	s_nop 1
	v_add_f32_dpp v164, v164, v164 row_ror:8 row_mask:0xf bank_mask:0xf
	s_nop 1
	v_add_f32_dpp v164, v164, v164 row_ror:4 row_mask:0xf bank_mask:0xf
	s_nop 1
	v_add_f32_dpp v164, v164, v164 row_ror:2 row_mask:0xf bank_mask:0xf
	s_nop 1
	v_add_f32_dpp v164, v164, v164 row_ror:1 row_mask:0xf bank_mask:0xf
	s_nop 0
	v_fmamk_f32 v164, v164, 0x3a800000, v200
	v_rsq_f32_e32 v164, v164
	s_nop 0
	v_pk_mul_f32 v[12:13], v[12:13], v[164:165] op_sel_hi:[1,0]
	v_pk_mul_f32 v[14:15], v[14:15], v[164:165] op_sel_hi:[1,0]
	v_pk_mul_f32 v[12:13], v[234:235], v[12:13]
	v_pk_mul_f32 v[14:15], v[236:237], v[14:15]
	s_waitcnt lgkmcnt(11)
; __device__ __forceinline__ unsigned pk2(float lo, float hi) { return pg8::cvt_pk_bf16(lo, hi); }
;     __device__ __forceinline__ void init(int N, int G, int c, int latent_only) { lat = latent_only; b.init(latent_only ? NB * SEQ : M, N, G, c); }
;     __device__ __forceinline__ void init(int c_, unsigned* cnt_) { lat.init(NB * SEQ, FF2, 1, 0); c = c_; cnt = cnt_; }
; __device__ __forceinline__ void row_pass(const RowPass& R, int gw, int ngw, int lane) {
;     ...
;     for (int row0 = gw; row0 < M; row0 += NR * ngw) {
;         f32x4 v[NR][4]; u32x2 yw[NR][4]; bool act[NR]; float* xrow[NR]; int bbs[NR];
; #pragma unroll
;         for (int k = 0; k < NR; ++k) {
;             const int row = row0 + k * ngw;
;             const int rowc = row < M ? row : row0;
;             const int b = rowc / RPB, i = rowc - b * RPB; const bool isctx = i < CTXL;
;             act[k] = (row < M) && !(isctx && R.skip_ctx);
;             bbs[k] = isctx ? 8 : b;
;             xrow[k] = isctx ? R.xc + ((size_t)b * CTXL + i) * DM : R.out + ((size_t)b * SEQ + (i - CTXL)) * DM;
;             const float* src = R.init ? (isctx ? R.ctx_in + ((size_t)b * CTXL + i) * DM : R.x_in + ((size_t)b * SEQ + (i - CTXL)) * DM) : xrow[k];
;             if (act[k]) {
; #pragma unroll
;                 for (int j = 0; j < 4; ++j) v[k][j] = __builtin_nontemporal_load((const f32x4*)(src + lane * 4 + 256 * j));
;                 if (R.update) { const bf16* yr = R.Y + (size_t)rowc * DM;
; #pragma unroll
;                     for (int j = 0; j < 4; ++j) yw[k][j] = __builtin_nontemporal_load((const u32x2*)(yr + lane * 4 + 256 * j)); }
;             }
;     ...
;                 const float rstd = __builtin_amdgcn_rsqf(wave_sum(ss) * (1.0f / DM) + EPS);
;                 const float* shift = R.mod + ((size_t)(R.ln * 9 + bb) * NMOD + R.si) * DM; const float* scale = shift + DM;
;                 bf16* hr = R.H + (size_t)row * DM;
; #pragma unroll
;                 for (int j = 0; j < 4; ++j) { const f32x4 gp = *(const f32x4*)(R.gpre + lane * 4 + 256 * j), sh = *(const f32x4*)(shift + lane * 4 + 256 * j), sc = *(const f32x4*)(scale + lane * 4 + 256 * j);
;                     const f32x4 hv = (v[k][j] * rstd * gp) * (sc + 1.0f) + sh;
;                     u32x2 w; w.x = pk2(hv[0], hv[1]); w.y = pk2(hv[2], hv[3]); *(u32x2*)(hr + lane * 4 + 256 * j) = w; }
;             }
	v_pk_add_f32 v[172:173], v[172:173], 1.0 op_sel_hi:[1,0]
	v_pk_add_f32 v[174:175], v[174:175], 1.0 op_sel_hi:[1,0]
	v_pk_fma_f32 v[12:13], v[172:173], v[12:13], v[80:81]
	v_pk_fma_f32 v[14:15], v[174:175], v[14:15], v[82:83]
	v_cvt_pk_bf16_f32 v12, v12, v13
	v_cvt_pk_bf16_f32 v13, v14, v15
	global_store_dwordx2 v[250:251], v[12:13], off offset:-1536
	ds_read_b128 v[80:83], v37 offset:20480
	v_pk_mul_f32 v[8:9], v[8:9], v[164:165] op_sel_hi:[1,0]
	v_pk_mul_f32 v[10:11], v[10:11], v[164:165] op_sel_hi:[1,0]
	v_pk_mul_f32 v[8:9], v[238:239], v[8:9]
	v_pk_mul_f32 v[10:11], v[240:241], v[10:11]
	s_waitcnt lgkmcnt(11)
	v_pk_add_f32 v[176:177], v[176:177], 1.0 op_sel_hi:[1,0]
	v_pk_add_f32 v[178:179], v[178:179], 1.0 op_sel_hi:[1,0]
	v_pk_fma_f32 v[8:9], v[176:177], v[8:9], v[84:85]
	v_pk_fma_f32 v[10:11], v[178:179], v[10:11], v[86:87]
	v_cvt_pk_bf16_f32 v8, v8, v9
	v_cvt_pk_bf16_f32 v9, v10, v11
	global_store_dwordx2 v[250:251], v[8:9], off offset:-1024
	ds_read_b128 v[84:87], v37 offset:21504
	v_pk_mul_f32 v[4:5], v[4:5], v[164:165] op_sel_hi:[1,0]
	v_pk_mul_f32 v[6:7], v[6:7], v[164:165] op_sel_hi:[1,0]
	v_pk_mul_f32 v[4:5], v[242:243], v[4:5]
	v_pk_mul_f32 v[6:7], v[244:245], v[6:7]
	s_waitcnt lgkmcnt(11)
	v_pk_add_f32 v[180:181], v[180:181], 1.0 op_sel_hi:[1,0]
	v_pk_add_f32 v[182:183], v[182:183], 1.0 op_sel_hi:[1,0]
	v_pk_fma_f32 v[4:5], v[180:181], v[4:5], v[88:89]
	v_pk_fma_f32 v[6:7], v[182:183], v[6:7], v[90:91]
	v_cvt_pk_bf16_f32 v4, v4, v5
	v_cvt_pk_bf16_f32 v5, v6, v7
	global_store_dwordx2 v[250:251], v[4:5], off offset:-512
	ds_read_b128 v[88:91], v37 offset:22528
	v_pk_mul_f32 v[0:1], v[0:1], v[164:165] op_sel_hi:[1,0]
	v_pk_mul_f32 v[2:3], v[2:3], v[164:165] op_sel_hi:[1,0]
	v_pk_mul_f32 v[0:1], v[246:247], v[0:1]
	v_pk_mul_f32 v[2:3], v[248:249], v[2:3]
	s_waitcnt lgkmcnt(11)
	v_pk_add_f32 v[184:185], v[184:185], 1.0 op_sel_hi:[1,0]
	v_pk_add_f32 v[186:187], v[186:187], 1.0 op_sel_hi:[1,0]
	v_pk_fma_f32 v[0:1], v[184:185], v[0:1], v[92:93]
	v_pk_fma_f32 v[2:3], v[186:187], v[2:3], v[94:95]
	v_cvt_pk_bf16_f32 v0, v0, v1
	v_cvt_pk_bf16_f32 v1, v2, v3
	global_store_dwordx2 v[250:251], v[0:1], off
	ds_read_b128 v[92:95], v37 offset:23552
	s_waitcnt vmcnt(8)
	s_mov_b32 s99, 0
	s_add_i32 s72, s19, s48
	s_cmp_gt_i32 s72, 0x87ff
	s_cbranch_scc1 .Lr3_slow_nopf
	s_add_i32 s8, s44, s72
	s_cmp_lt_i32 s8, 0x8800
	s_cbranch_scc0 .Lr3_slow_nopf
	s_mov_b32 s41, s72
	s_mul_hi_i32 s6, s41, 0x78787879
	s_lshr_b32 s7, s6, 31
	s_ashr_i32 s6, s6, 11
	s_add_i32 s6, s6, s7
	s_mul_i32 s7, s6, 0xffffef00
	s_add_i32 s7, s41, s7
	s_cmpk_gt_i32 s7, 0xff
	s_cselect_b64 s[50:51], -1, 0
	s_mul_hi_i32 s9, s8, 0x78787879
	s_lshr_b32 s25, s9, 31
	s_ashr_i32 s9, s9, 11
	s_add_i32 s9, s9, s25
	s_mul_i32 s25, s9, 0xffffef00
	s_add_i32 s25, s8, s25
	s_cmpk_gt_i32 s25, 0xff
	s_cselect_b64 s[52:53], -1, 0
	s_cmp_lg_u64 s[4:5], 0
	s_cbranch_scc0 .Lr3_slow_nopf
	s_add_i32 s72, s7, 0xffffff00
	s_cmp_lg_u64 s[50:51], 0
	s_cselect_b32 s27, s22, s49
	s_cselect_b32 s32, s23, s55
	s_cselect_b32 s37, 24, 20
	s_cselect_b32 s72, s72, s7
	s_cselect_b32 s85, s6, 8
	s_mov_b32 s40, s6
	s_mov_b32 s41, 0
	s_lshl_b64 s[40:41], s[40:41], s37
	s_add_u32 s40, s27, s40
	s_addc_u32 s41, s32, s41
	s_lshl_b32 s72, s72, 12
	s_add_u32 s40, s40, s72
	s_addc_u32 s41, s41, 0
	s_add_i32 s27, s85, s3
	s_mul_hi_i32 s32, s27, 0x6000
	s_mulk_i32 s27, 0x6000
	s_add_u32 s66, s34, s27
	s_addc_u32 s67, s35, s32
	s_add_u32 s66, s66, 0x5000
	s_addc_u32 s67, s67, 0
	s_add_i32 s27, s85, s13
	s_mul_hi_i32 s32, s27, 0x6000
	s_mulk_i32 s27, 0x6000
	s_add_u32 s38, s34, s27
	s_addc_u32 s39, s35, s32
	s_add_u32 s46, s38, 0x1000
	s_addc_u32 s47, s39, 0
	s_mov_b64 s[6:7], s[52:53]
	s_cmp_lg_u64 s[6:7], 0
	s_cselect_b32 s85, s9, 8
	s_add_i32 s27, s85, s3
	s_mul_hi_i32 s32, s27, 0x6000
	s_mulk_i32 s27, 0x6000
	s_add_u32 s10, s34, s27
	s_addc_u32 s11, s35, s32
	s_add_u32 s10, s10, 0x5000
	s_addc_u32 s11, s11, 0
	s_add_i32 s27, s85, s13
	s_mul_hi_i32 s32, s27, 0x6000
	s_mulk_i32 s27, 0x6000
	s_add_u32 s50, s34, s27
	s_addc_u32 s51, s35, s32
	s_add_u32 s52, s50, 0x1000
	s_addc_u32 s53, s51, 0
	s_xor_b32 s25, s93, 0x6000
	v_lshl_add_u64 v[250:251], v[46:47], 0, s[74:75]
	global_load_dwordx4 v[12:15], v160, s[40:41] nt
	global_load_dwordx4 v[8:11], v160, s[40:41] offset:1024 nt
	global_load_dwordx4 v[4:7], v160, s[40:41] offset:2048 nt
	global_load_dwordx4 v[0:3], v160, s[40:41] offset:3072 nt
	global_load_dwordx2 v[54:55], v[250:251], off offset:-1536 nt
	global_load_dwordx2 v[52:53], v[250:251], off offset:-1024 nt
	global_load_dwordx2 v[50:51], v[250:251], off offset:-512 nt
	global_load_dwordx2 v[48:49], v[250:251], off nt
	s_and_b32 s72, s19, 7
	s_and_b32 s85, s72, 3
	s_lshl_b32 s85, s85, 10
	s_lshl_b32 s37, s72, 10
	s_add_i32 s37, s37, s25
	s_cmp_lt_u32 s72, 4
	s_cselect_b32 s6, s66, s38
	s_cselect_b32 s7, s67, s39
	s_cselect_b32 s8, s46, s10
	s_cselect_b32 s9, s47, s11
	s_cselect_b32 s26, s50, s52
	s_cselect_b32 s27, s51, s53
	s_add_u32 s6, s6, s85
	s_addc_u32 s7, s7, 0
	s_add_u32 s8, s8, s85
	s_addc_u32 s9, s9, 0
	s_add_u32 s26, s26, s85
	s_addc_u32 s27, s27, 0
	s_mov_b32 m0, s37
	s_nop 0
	global_load_lds_dwordx4 v160, s[6:7]
	s_add_i32 s37, s37, 0x2000
	s_mov_b32 m0, s37
	s_nop 0
	global_load_lds_dwordx4 v160, s[8:9]
	s_add_i32 s37, s37, 0x2000
	s_mov_b32 m0, s37
	s_nop 0
	global_load_lds_dwordx4 v160, s[26:27]
	s_mov_b32 s99, 1
